# stack on best: skip finishSM VALU for tiles the wave did not attend + attention/gMLP phase-order stagger across workgroup groups
# baseline (speedup 1.0000x reference)
; __device__ __forceinline__ void finishSM(f32x16& p0, f32x16& p1, float alpha, float& l_reg, bf16x8& pa0, bf16x8& pa1, bf16x8& pa2, bf16x8& pa3) {
;     for (int r = 0; r < 16; ++r) p1[r] = __builtin_amdgcn_exp2f(p1[r]);
;     float ps = 0; for (int r = 0; r < 16; ++r) ps += p0[r]; for (int r = 0; r < 16; ++r) ps += p1[r];
;     { auto rr = __builtin_amdgcn_permlane32_swap(__float_as_uint(ps), __float_as_uint(ps), false, false);
;       ps = __uint_as_float(rr[0]) + __uint_as_float(rr[1]); }
;     l_reg = l_reg * alpha + ps;
;     ...
;     PK4(p0, 0, pa0); PK4(p0, 8, pa1); PK4(p1, 0, pa2); PK4(p1, 8, pa3);
;     ...
; }
.LBB0_242:
	s_cmp_le_i32 s60, s55
	s_cselect_b64 s[66:67], -1, 0
	s_add_i32 s68, s60, 63
	s_cmp_ge_i32 s68, s56
	s_cselect_b64 s[68:69], -1, 0
	s_and_b64 s[66:67], s[66:67], s[68:69]
	s_cmp_lg_u64 s[66:67], 0
	s_cbranch_scc1 .Lfsm_A_do
	v_mov_b32_e32 v232, 0
	v_mov_b32_e32 v233, 0
	s_branch .Lfsm_A_done

; template <int VB, bool SK>
; __device__ __forceinline__ void pv_tile(f32x16* o, int vb0, bf16x8 pa0, bf16x8 pa1, bf16x8 pa2, bf16x8 pa3, bool act) {
;     if (SK && !act) return;
;     ...
;     PV_D0(0); PV_D0(1); PV_D0(2); PV_D0(3);
.Lfsm_A_done:
	v_add_u32_e32 v235, s60, v203
	v_add_u32_e32 v1, 0x80, v235
	v_mad_i64_i32 v[14:15], s[38:39], v1, s48, 0
	v_add_u32_e32 v1, 0xa0, v235
	v_lshlrev_b64 v[14:15], 1, v[14:15]
	v_mad_i64_i32 v[118:119], s[38:39], v1, s48, 0
	v_lshl_add_u64 v[116:117], v[204:205], 0, v[14:15]
	v_lshlrev_b64 v[118:119], 1, v[118:119]
	v_lshl_add_u64 v[14:15], v[206:207], 0, v[14:15]
	v_lshl_add_u64 v[120:121], v[204:205], 0, v[118:119]
	global_load_dwordx4 v[176:179], v[116:117], off
	global_load_dwordx4 v[180:183], v[120:121], off
	v_lshl_add_u64 v[116:117], v[206:207], 0, v[118:119]
	global_load_dwordx4 v[184:187], v[14:15], off
	global_load_dwordx4 v[188:191], v[116:117], off
	s_cmp_le_i32 s60, s55
	s_cselect_b64 s[38:39], -1, 0
	s_add_i32 s61, s60, 63
	s_cmp_ge_i32 s61, s56
	s_cselect_b64 s[62:63], -1, 0
	s_and_b64 s[38:39], s[38:39], s[62:63]
	s_andn2_b64 vcc, exec, s[38:39]
	s_cbranch_vccnz .LBB0_244
	ds_read_b64_tr_b16 v[116:117], v215 offset:0
	ds_read_b64_tr_b16 v[118:119], v215 offset:0x800
	ds_read_b64_tr_b16 v[120:121], v215 offset:0x1000
	ds_read_b64_tr_b16 v[122:123], v215 offset:0x1800
	s_waitcnt vmcnt(4)
	ds_read_b64_tr_b16 v[124:125], v215 offset:0x2000
	ds_read_b64_tr_b16 v[126:127], v215 offset:0x2800
	ds_read_b64_tr_b16 v[128:129], v215 offset:0x3000
	ds_read_b64_tr_b16 v[130:131], v215 offset:0x3800
	s_waitcnt lgkmcnt(6)
	v_mfma_f32_32x32x16_bf16 v[64:79], v[2:5], v[116:119], v[64:79]
	ds_read_b64_tr_b16 v[116:117], v215 offset:0x200
	ds_read_b64_tr_b16 v[118:119], v215 offset:0xa00
	s_waitcnt lgkmcnt(6)
	v_mfma_f32_32x32x16_bf16 v[64:79], v[6:9], v[120:123], v[64:79]
	ds_read_b64_tr_b16 v[120:121], v215 offset:0x1200
	ds_read_b64_tr_b16 v[122:123], v215 offset:0x1a00
	s_waitcnt lgkmcnt(6)
	v_mfma_f32_32x32x16_bf16 v[64:79], v[10:13], v[124:127], v[64:79]
	ds_read_b64_tr_b16 v[124:125], v215 offset:0x2200
	ds_read_b64_tr_b16 v[126:127], v215 offset:0x2a00
	s_waitcnt lgkmcnt(6)
	v_mfma_f32_32x32x16_bf16 v[64:79], v[80:83], v[128:131], v[64:79]
	ds_read_b64_tr_b16 v[128:129], v215 offset:0x3200
	ds_read_b64_tr_b16 v[130:131], v215 offset:0x3a00
	s_waitcnt lgkmcnt(6)
	v_mfma_f32_32x32x16_bf16 v[48:63], v[2:5], v[116:119], v[48:63]
	ds_read_b64_tr_b16 v[116:117], v215 offset:0x400
	ds_read_b64_tr_b16 v[118:119], v215 offset:0xc00
	s_waitcnt lgkmcnt(6)
	v_mfma_f32_32x32x16_bf16 v[48:63], v[6:9], v[120:123], v[48:63]
	ds_read_b64_tr_b16 v[120:121], v215 offset:0x1400
	ds_read_b64_tr_b16 v[122:123], v215 offset:0x1c00
	s_waitcnt lgkmcnt(6)
	v_mfma_f32_32x32x16_bf16 v[48:63], v[10:13], v[124:127], v[48:63]
	ds_read_b64_tr_b16 v[124:125], v215 offset:0x2400
	ds_read_b64_tr_b16 v[126:127], v215 offset:0x2c00
	s_waitcnt lgkmcnt(6)
	v_mfma_f32_32x32x16_bf16 v[48:63], v[80:83], v[128:131], v[48:63]
	ds_read_b64_tr_b16 v[128:129], v215 offset:0x3400
	ds_read_b64_tr_b16 v[130:131], v215 offset:0x3c00
	s_waitcnt lgkmcnt(6)
	v_mfma_f32_32x32x16_bf16 v[32:47], v[2:5], v[116:119], v[32:47]
	ds_read_b64_tr_b16 v[116:117], v215 offset:0x600
	ds_read_b64_tr_b16 v[118:119], v215 offset:0xe00
	s_waitcnt lgkmcnt(6)
	v_mfma_f32_32x32x16_bf16 v[32:47], v[6:9], v[120:123], v[32:47]
	ds_read_b64_tr_b16 v[120:121], v215 offset:0x1600
	ds_read_b64_tr_b16 v[122:123], v215 offset:0x1e00
	s_waitcnt lgkmcnt(6)
	v_mfma_f32_32x32x16_bf16 v[32:47], v[10:13], v[124:127], v[32:47]
	ds_read_b64_tr_b16 v[124:125], v215 offset:0x2600
	ds_read_b64_tr_b16 v[126:127], v215 offset:0x2e00
	s_waitcnt lgkmcnt(6)
	v_mfma_f32_32x32x16_bf16 v[32:47], v[80:83], v[128:131], v[32:47]
	ds_read_b64_tr_b16 v[128:129], v215 offset:0x3600
	ds_read_b64_tr_b16 v[130:131], v215 offset:0x3e00
	s_waitcnt lgkmcnt(6)
	v_mfma_f32_32x32x16_bf16 v[16:31], v[2:5], v[116:119], v[16:31]
	s_waitcnt lgkmcnt(4)
	v_mfma_f32_32x32x16_bf16 v[16:31], v[6:9], v[120:123], v[16:31]
	s_waitcnt lgkmcnt(2)
	v_mfma_f32_32x32x16_bf16 v[16:31], v[10:13], v[124:127], v[16:31]
	s_waitcnt lgkmcnt(0)
	v_mfma_f32_32x32x16_bf16 v[16:31], v[80:83], v[128:131], v[16:31]

; __device__ __forceinline__ void finishSM(f32x16& p0, f32x16& p1, float alpha, float& l_reg, bf16x8& pa0, bf16x8& pa1, bf16x8& pa2, bf16x8& pa3) {
;     for (int r = 0; r < 16; ++r) p1[r] = __builtin_amdgcn_exp2f(p1[r]);
;     float ps = 0; for (int r = 0; r < 16; ++r) ps += p0[r]; for (int r = 0; r < 16; ++r) ps += p1[r];
;     { auto rr = __builtin_amdgcn_permlane32_swap(__float_as_uint(ps), __float_as_uint(ps), false, false);
;       ps = __uint_as_float(rr[0]) + __uint_as_float(rr[1]); }
;     l_reg = l_reg * alpha + ps;
.LBB0_254:
	s_and_b64 s[66:67], exec, s[8:9]
	s_cbranch_scc0 .Lfsm_B_do
	v_mov_b32_e32 v1, 0
	v_mov_b32_e32 v14, 0
	s_branch .Lfsm_B_done

.Lfsm_B_done:
	s_add_i32 s62, s59, 1
	s_cmp_lt_i32 s62, s57
	s_cselect_b64 s[38:39], -1, 0
	s_cmp_ge_i32 s62, s57
	s_cbranch_scc0 .LBB0_257
	s_and_b64 vcc, exec, s[8:9]
	s_cbranch_vccz .LBB0_258
